# fox unit epilogue: the 8 serial gate load/wait/store round trips replaced by 8 loads issued up front with counted waits
# baseline (speedup 1.0000x reference)
; __device__ __forceinline__ unsigned cvtpk(float lo, float hi) { f32x2 v = {lo, hi}; bf16x2_t b = __builtin_convertvector(v, bf16x2_t); return __builtin_bit_cast(unsigned, b); }
; __device__ __forceinline__ float bf_lo(unsigned u) { return __uint_as_float(u << 16); }
; __device__ __forceinline__ float bf_hi(unsigned u) { return __uint_as_float(u & 0xffff0000u); }
; __device__ __forceinline__ float swap32_sum(float m) { auto rr = __builtin_amdgcn_permlane32_swap(__float_as_uint(m), __float_as_uint(m), false, false); return __uint_as_float(rr[0]) + __uint_as_float(rr[1]); }
; template <bool DIFF>
; __device__ __forceinline__ void attn_unit(const AttnP& A, int b, int h, int qi, ldsp lds) {
;     ...
;     const float lt = swap32_sum(l_run);
;     const float inv = lt > 0.f ? 1.0f / lt : 0.f;
;     const size_t Rq = Rb + q_pp;
;     bf16* mrow = (qi != 0) ? A.mixed + ((size_t)b * T + (q_pp - 64)) * DM : A.mixm + (size_t)((q_pp - 48) & 15) * DM;
;     if (!DIFF) {
;         if (store_ok) {
; #pragma unroll
;             for (int t = 0; t < NTD; ++t)
; #pragma unroll
;                 for (int g = 0; g < 4; ++g) {
;                     const int dv0 = 32 * t + 8 * g + 4 * hi;
;                     const u32x2 z = *(const u32x2*)(A.P + Rq * NP + zcol + dv0);
;                     u32x2 wv; wv.x = cvtpk(o[t][4 * g] * inv * bf_lo(z.x), o[t][4 * g + 1] * inv * bf_hi(z.x)); wv.y = cvtpk(o[t][4 * g + 2] * inv * bf_lo(z.y), o[t][4 * g + 3] * inv * bf_hi(z.y));
;                     *(u32x2*)(mrow + mcol + dv0) = wv;
;                 }
;         }
.LBB0_492:
	s_cmpk_lt_u32 s90, 0x108
	v_and_b32_e32 v0, -16, v146
	s_cselect_b64 s[0:1], -1, 0
	v_cmp_eq_u32_e32 vcc, 48, v0
	s_and_b64 s[0:1], s[0:1], vcc
	s_or_b64 s[0:1], s[16:17], s[0:1]
	s_and_saveexec_b64 s[16:17], s[0:1]
	s_xor_b64 s[0:1], exec, s[16:17]
	s_cbranch_execz .LBB0_494
	s_mov_b64 s[16:17], 0x1c00
	v_lshl_add_u64 v[34:35], v[144:145], 0, s[16:17]
	v_lshlrev_b32_e32 v0, 1, v151
	v_lshl_add_u64 v[40:41], v[34:35], 0, v[0:1]
	global_load_dwordx2 v[116:117], v[40:41], off
	global_load_dwordx2 v[118:119], v[40:41], off offset:16
	global_load_dwordx2 v[120:121], v[40:41], off offset:32
	global_load_dwordx2 v[122:123], v[40:41], off offset:48
	global_load_dwordx2 v[124:125], v[40:41], off offset:64
	global_load_dwordx2 v[126:127], v[40:41], off offset:80
	global_load_dwordx2 v[128:129], v[40:41], off offset:96
	global_load_dwordx2 v[130:131], v[40:41], off offset:112
	v_add_f32_e32 v42, v154, v38
	v_div_scale_f32 v43, s[16:17], v42, v42, 1.0
	v_rcp_f32_e32 v45, v43
	v_div_scale_f32 v44, vcc, 1.0, v42, 1.0
	s_lshl_b32 s34, s92, 1
	v_fma_f32 v46, -v43, v45, 1.0
	v_fmac_f32_e32 v45, v46, v45
	v_mul_f32_e32 v46, v44, v45
	v_fma_f32 v47, -v43, v46, v44
	v_fmac_f32_e32 v46, v47, v45
	v_fma_f32 v43, -v43, v46, v44
	v_div_fmas_f32 v43, v43, v45, v46
	v_div_fixup_f32 v43, v43, v42, 1.0
	v_cmp_lt_f32_e32 vcc, 0, v42
	v_lshl_add_u64 v[36:37], v[36:37], 0, s[34:35]
	v_mov_b32_e32 v39, v1
	v_cndmask_b32_e32 v42, 0, v43, vcc
	v_pk_mul_f32 v[18:19], v[18:19], v[42:43] op_sel_hi:[1,0]
	v_pk_mul_f32 v[20:21], v[20:21], v[42:43] op_sel_hi:[1,0]
	v_or_b32_e32 v38, 16, v0
	v_lshl_add_u64 v[36:37], v[36:37], 0, v[0:1]
	v_lshl_add_u64 v[38:39], v[34:35], 0, v[38:39]
	v_pk_mul_f32 v[22:23], v[22:23], v[42:43] op_sel_hi:[1,0]
	v_pk_mul_f32 v[24:25], v[24:25], v[42:43] op_sel_hi:[1,0]
	v_pk_mul_f32 v[2:3], v[2:3], v[42:43] op_sel_hi:[1,0]
	v_pk_mul_f32 v[4:5], v[4:5], v[42:43] op_sel_hi:[1,0]
	v_pk_mul_f32 v[6:7], v[6:7], v[42:43] op_sel_hi:[1,0]
	v_pk_mul_f32 v[8:9], v[8:9], v[42:43] op_sel_hi:[1,0]
	s_waitcnt vmcnt(7)
	v_lshlrev_b32_e32 v44, 16, v116
	v_and_b32_e32 v45, 0xffff0000, v116
	v_lshlrev_b32_e32 v40, 16, v117
	v_and_b32_e32 v41, 0xffff0000, v117
	v_pk_mul_f32 v[18:19], v[18:19], v[44:45]
	v_pk_mul_f32 v[20:21], v[20:21], v[40:41]
	v_cvt_pk_bf16_f32 v18, v18, v19
	v_cvt_pk_bf16_f32 v19, v20, v21
	global_store_dwordx2 v[36:37], v[18:19], off offset:1024
	s_nop 1
	v_mov_b32_e32 v21, v1
	v_or_b32_e32 v20, 32, v0
	v_lshl_add_u64 v[20:21], v[34:35], 0, v[20:21]
	s_waitcnt vmcnt(7)
	v_lshlrev_b32_e32 v38, 16, v118
	v_and_b32_e32 v39, 0xffff0000, v118
	v_lshlrev_b32_e32 v18, 16, v119
	v_and_b32_e32 v19, 0xffff0000, v119
	v_pk_mul_f32 v[22:23], v[22:23], v[38:39]
	v_pk_mul_f32 v[18:19], v[24:25], v[18:19]
	v_cvt_pk_bf16_f32 v22, v22, v23
	v_cvt_pk_bf16_f32 v23, v18, v19
	global_store_dwordx2 v[36:37], v[22:23], off offset:1040
	s_nop 1
	v_pk_mul_f32 v[22:23], v[26:27], v[42:43] op_sel_hi:[1,0]
	v_pk_mul_f32 v[24:25], v[28:29], v[42:43] op_sel_hi:[1,0]
	v_mov_b32_e32 v21, v1
	v_or_b32_e32 v20, 48, v0
	v_lshl_add_u64 v[20:21], v[34:35], 0, v[20:21]
	s_waitcnt vmcnt(7)
	v_lshlrev_b32_e32 v26, 16, v120
	v_and_b32_e32 v27, 0xffff0000, v120
	v_lshlrev_b32_e32 v18, 16, v121
	v_and_b32_e32 v19, 0xffff0000, v121
	v_pk_mul_f32 v[22:23], v[22:23], v[26:27]
	v_pk_mul_f32 v[18:19], v[24:25], v[18:19]
	v_cvt_pk_bf16_f32 v22, v22, v23
	v_cvt_pk_bf16_f32 v23, v18, v19
	global_store_dwordx2 v[36:37], v[22:23], off offset:1056
	s_nop 1
	v_pk_mul_f32 v[22:23], v[30:31], v[42:43] op_sel_hi:[1,0]
	v_pk_mul_f32 v[24:25], v[32:33], v[42:43] op_sel_hi:[1,0]
	v_mov_b32_e32 v21, v1
	v_or_b32_e32 v20, 64, v0
	v_lshl_add_u64 v[20:21], v[34:35], 0, v[20:21]
	s_waitcnt vmcnt(7)
	v_lshlrev_b32_e32 v26, 16, v122
	v_and_b32_e32 v27, 0xffff0000, v122
	v_lshlrev_b32_e32 v18, 16, v123
	v_and_b32_e32 v19, 0xffff0000, v123
	v_pk_mul_f32 v[22:23], v[22:23], v[26:27]
	v_pk_mul_f32 v[18:19], v[24:25], v[18:19]
	v_cvt_pk_bf16_f32 v22, v22, v23
	v_cvt_pk_bf16_f32 v23, v18, v19
	global_store_dwordx2 v[36:37], v[22:23], off offset:1072
	s_nop 1
	v_mov_b32_e32 v21, v1
	v_or_b32_e32 v20, 0x50, v0
	v_lshl_add_u64 v[20:21], v[34:35], 0, v[20:21]
	s_waitcnt vmcnt(7)
	v_lshlrev_b32_e32 v22, 16, v124
	v_and_b32_e32 v23, 0xffff0000, v124
	v_lshlrev_b32_e32 v18, 16, v125
	v_and_b32_e32 v19, 0xffff0000, v125
	v_pk_mul_f32 v[2:3], v[2:3], v[22:23]
	v_pk_mul_f32 v[4:5], v[4:5], v[18:19]
	v_cvt_pk_bf16_f32 v2, v2, v3
	v_cvt_pk_bf16_f32 v3, v4, v5
	global_store_dwordx2 v[36:37], v[2:3], off offset:1088
	s_nop 1
	v_mov_b32_e32 v5, v1
	v_or_b32_e32 v4, 0x60, v0
	v_lshl_add_u64 v[4:5], v[34:35], 0, v[4:5]
	v_or_b32_e32 v0, 0x70, v0
	s_waitcnt vmcnt(7)
	v_lshlrev_b32_e32 v18, 16, v126
	v_and_b32_e32 v19, 0xffff0000, v126
	v_lshlrev_b32_e32 v2, 16, v127
	v_and_b32_e32 v3, 0xffff0000, v127
	v_pk_mul_f32 v[6:7], v[6:7], v[18:19]
	v_pk_mul_f32 v[2:3], v[8:9], v[2:3]
	v_cvt_pk_bf16_f32 v6, v6, v7
	v_cvt_pk_bf16_f32 v7, v2, v3
	global_store_dwordx2 v[36:37], v[6:7], off offset:1104
	s_nop 1
	v_pk_mul_f32 v[6:7], v[10:11], v[42:43] op_sel_hi:[1,0]
	v_pk_mul_f32 v[8:9], v[12:13], v[42:43] op_sel_hi:[1,0]
	v_lshl_add_u64 v[4:5], v[34:35], 0, v[0:1]
	s_waitcnt vmcnt(7)
	v_lshlrev_b32_e32 v10, 16, v128
	v_and_b32_e32 v11, 0xffff0000, v128
	v_lshlrev_b32_e32 v2, 16, v129
	v_and_b32_e32 v3, 0xffff0000, v129
	v_pk_mul_f32 v[6:7], v[6:7], v[10:11]
	v_pk_mul_f32 v[2:3], v[8:9], v[2:3]
	v_cvt_pk_bf16_f32 v6, v6, v7
	v_cvt_pk_bf16_f32 v7, v2, v3
	global_store_dwordx2 v[36:37], v[6:7], off offset:1120
	s_nop 1
	v_pk_mul_f32 v[4:5], v[14:15], v[42:43] op_sel_hi:[1,0]
	v_pk_mul_f32 v[6:7], v[16:17], v[42:43] op_sel_hi:[1,0]
	s_waitcnt vmcnt(7)
	v_lshlrev_b32_e32 v8, 16, v130
	v_and_b32_e32 v9, 0xffff0000, v130
	v_lshlrev_b32_e32 v2, 16, v131
	v_and_b32_e32 v3, 0xffff0000, v131
	v_pk_mul_f32 v[4:5], v[4:5], v[8:9]
	v_pk_mul_f32 v[2:3], v[6:7], v[2:3]
	v_cvt_pk_bf16_f32 v4, v4, v5
	v_cvt_pk_bf16_f32 v5, v2, v3
	global_store_dwordx2 v[36:37], v[4:5], off offset:1136
